# v012 (without the MLP-up accumulator clears) plus: MLP-up stages the weight rows so a wave's two 32-column halves are adjacent and re-cuts each store pair with a row rotate into two stores of 8 rows x
# speedup vs baseline: 1.0004x; 1.0004x over previous
.LBB0_548:
	s_or_b64 exec, exec, s[12:13]
	v_readlane_b32 s18, v255, 54
	s_mov_b64 s[14:15], s[82:83]
	s_mov_b64 s[12:13], s[82:83]
	s_mov_b64 s[40:41], s[82:83]
	v_mov_b32_e32 v16, v224
	v_readlane_b32 s19, v255, 55
	s_waitcnt lgkmcnt(0)
	s_barrier
	s_and_b64 vcc, exec, s[18:19]
	v_readfirstlane_b32 s20, v16
	s_cbranch_vccz .LBB0_568
	v_lshlrev_b32_e32 v0, 4, v16
	v_add_u32_e32 v2, 0x2000, v0
	v_ashrrev_i32_e32 v3, 31, v2
	v_lshrrev_b32_e32 v3, 22, v3
	v_add_u32_e32 v3, v2, v3
	v_ashrrev_i32_e32 v10, 10, v3
	v_mul_i32_i24_e32 v3, 0x400, v10
	v_sub_u32_e32 v2, v2, v3
	v_lshrrev_b32_e32 v3, 4, v2
	v_bitop3_b32 v2, v3, v2, 32 bitop3:0x6c
	s_add_u32 s0, s14, 0x4000000
	v_ashrrev_i32_e32 v3, 31, v2
	s_addc_u32 s17, s15, 0
	v_readlane_b32 s14, v254, 36
	v_lshrrev_b32_e32 v3, 26, v3
	s_lshl_b32 s14, s14, 23
	v_add_u32_e32 v3, v2, v3
	v_lshlrev_b32_e32 v4, 3, v10
	s_add_u32 s12, s12, s14
	v_ashrrev_i32_e32 v11, 6, v3
	v_and_b32_e32 v4, -16, v4
	s_addc_u32 s13, s13, 0
	v_add_u32_e32 v4, v11, v4
	s_add_u32 s56, s12, 0x1400000
	v_and_b32_e32 v5, 3, v11
	s_mov_b32 s12, 0x1fffe0
	v_lshrrev_b32_e32 v6, 2, v4
	v_lshlrev_b32_e32 v7, 1, v4
	v_and_or_b32 v5, v4, s12, v5
	v_and_b32_e32 v6, 4, v6
	v_and_b32_e32 v7, 24, v7
	v_and_b32_e32 v3, 0xc0, v3
	v_or3_b32 v5, v5, v6, v7
	v_sub_u32_e32 v2, v2, v3
	v_mov_b32_e32 v7, 1
	v_lshlrev_b32_e32 v6, 5, v10
	v_ashrrev_i16_sdwa v2, v7, sext(v2) dst_sel:DWORD dst_unused:UNUSED_PAD src0_sel:DWORD src1_sel:BYTE_0
	v_and_b32_e32 v6, 32, v6
	v_bfe_i32 v12, v2, 0, 16
	v_add_lshl_u32 v2, v6, v12, 1
	v_lshl_add_u32 v130, v5, 11, v2
	v_lshl_add_u32 v132, v4, 11, v2
	v_bfe_i32 v2, v16, 27, 1
	v_lshrrev_b32_e32 v2, 22, v2
	v_add_u32_e32 v2, v0, v2
	v_and_b32_e32 v2, 0xfffffc00, v2
	v_sub_u32_e32 v0, v0, v2
	v_lshrrev_b32_e32 v2, 4, v0
	v_ashrrev_i32_e32 v3, 31, v16
	v_bitop3_b32 v0, v2, v0, 32 bitop3:0x6c
	v_lshrrev_b32_e32 v3, 26, v3
	v_ashrrev_i32_e32 v2, 31, v0
	v_add_u32_e32 v3, v16, v3
	v_lshrrev_b32_e32 v2, 26, v2
	v_ashrrev_i32_e32 v14, 6, v3
	v_add_u32_e32 v2, v0, v2
	v_lshlrev_b32_e32 v3, 3, v14
	v_ashrrev_i32_e32 v13, 6, v2
	v_and_b32_e32 v3, -16, v3
	v_add_u32_e32 v3, v13, v3
	v_and_b32_e32 v4, 3, v13
	v_lshrrev_b32_e32 v5, 2, v3
	v_lshlrev_b32_e32 v6, 1, v3
	v_and_b32_e32 v2, 0xc0, v2
	s_addc_u32 s57, s13, 0
	s_ashr_i32 s21, s20, 6
	v_and_or_b32 v4, v3, s12, v4
	v_and_b32_e32 v5, 4, v5
	v_and_b32_e32 v6, 24, v6
	v_sub_u32_e32 v0, v0, v2
	s_ashr_i32 s28, s20, 8
	s_lshl_b32 s58, s21, 10
	v_or3_b32 v4, v4, v5, v6
	v_lshlrev_b32_e32 v5, 5, v14
	v_ashrrev_i16_sdwa v0, v7, sext(v0) dst_sel:DWORD dst_unused:UNUSED_PAD src0_sel:DWORD src1_sel:BYTE_0
	v_readlane_b32 s12, v255, 57
	v_and_b32_e32 v5, 32, v5
	v_bfe_i32 v15, v0, 0, 16
	v_readlane_b32 s13, v255, 58
	s_add_u32 s12, s56, s12
	v_add_lshl_u32 v2, v5, v15, 1
	s_addc_u32 s13, s57, s13
	s_add_i32 s59, s58, 0
	v_lshl_add_u32 v0, v4, 11, v2
	v_lshrrev_b32_e32 v248, 8, v224
	v_lshl_add_u32 v0, v248, 16, v0
	v_lshl_add_u32 v130, v248, 16, v130
	v_add_u32_e32 v130, 0x20000, v130
	s_add_i32 m0, s59, 0x10000
	v_readlane_b32 s15, v254, 37
	global_load_lds_dwordx4 v0, s[12:13]
	s_add_i32 m0, s59, 0x12000
	s_add_u32 s14, s12, 0x10000
	global_load_lds_dwordx4 v130, s[12:13]
	s_addc_u32 s15, s13, 0
	s_add_i32 m0, s59, 0x14000
	v_lshl_add_u32 v134, v3, 11, v2
	global_load_lds_dwordx4 v0, s[14:15]
	s_add_i32 m0, s59, 0x16000
	v_mov_b32_e32 v131, v1
	global_load_lds_dwordx4 v130, s[14:15]
	v_readlane_b32 s14, v254, 1
	v_readlane_b32 s15, v254, 2
	s_add_u32 s14, s0, s14
	s_addc_u32 s15, s17, s15
	s_add_i32 s60, s59, 0x2000
	s_mov_b32 m0, s59
	s_add_u32 s18, s14, 0x40000
	global_load_lds_dwordx4 v134, s[14:15]
	s_mov_b32 m0, s60
	s_addc_u32 s19, s15, 0
	s_add_i32 s61, s59, 0x4000
	global_load_lds_dwordx4 v132, s[14:15]
	s_mov_b32 m0, s61
	s_add_i32 s62, s59, 0x6000
	global_load_lds_dwordx4 v134, s[18:19]
	s_mov_b32 m0, s62
	v_mov_b32_e32 v135, v1
	global_load_lds_dwordx4 v132, s[18:19]
	v_mov_b32_e32 v133, v1
	s_cmp_eq_u32 s28, 1
	v_lshl_add_u64 v[8:9], s[12:13], 0, v[0:1]
	v_lshl_add_u64 v[6:7], s[12:13], 0, v[130:131]
	v_lshl_add_u64 v[2:3], s[14:15], 0, v[134:135]
	s_cselect_b64 s[18:19], -1, 0
	s_cmp_lg_u32 s28, 1
	v_lshl_add_u64 v[4:5], s[14:15], 0, v[132:133]
	s_cbranch_scc1 .LBB0_551
	s_barrier
.LBB0_551:
	v_lshrrev_b32_e32 v18, 1, v16
	s_add_u32 s42, s40, 0x18000000
	v_and_b32_e32 v18, 24, v18
	s_addc_u32 s43, s41, 0
	v_and_b32_e32 v17, 15, v16
	v_lshlrev_b32_e32 v19, 1, v18
	v_lshlrev_b32_e32 v16, 2, v16
	s_lshl_b32 s21, s21, 5
	v_lshl_or_b32 v141, s28, 6, v17
	v_lshl_or_b32 v17, v17, 6, v19
	s_lshl_b32 s28, s28, 13
	v_and_b32_e32 v16, 32, v16
	s_and_b32 s21, s21, 0x60
	s_add_i32 m0, s59, 0x18000
	v_lshl_add_u64 v[8:9], v[8:9], 0, s[10:11]
	v_bitop3_b32 v19, v17, s28, v16 bitop3:0xde
	s_lshl_b32 s28, s21, 7
	s_waitcnt vmcnt(2)
	s_barrier
	global_load_lds_dwordx4 v[8:9], off
	v_lshl_add_u64 v[6:7], v[6:7], 0, s[10:11]
	s_add_i32 m0, s59, 0x1a000
	s_add_i32 s63, s59, 0x8000
	s_add_i32 s64, s59, 0xa000
	v_bitop3_b32 v145, v17, s28, v16 bitop3:0xde
	global_load_lds_dwordx4 v[6:7], off
	v_lshl_add_u64 v[2:3], v[2:3], 0, s[10:11]
	s_mov_b32 m0, s63
	s_add_u32 s28, s12, 0x10080
	global_load_lds_dwordx4 v[2:3], off
	v_lshl_add_u64 v[2:3], v[4:5], 0, s[10:11]
	s_mov_b32 m0, s64
	s_addc_u32 s29, s13, 0
	global_load_lds_dwordx4 v[2:3], off
	s_add_i32 m0, s59, 0x1c000
	v_lshl_add_u64 v[2:3], s[28:29], 0, v[0:1]
	global_load_lds_dwordx4 v[2:3], off
	v_lshl_add_u64 v[2:3], s[28:29], 0, v[130:131]
	s_add_i32 m0, s59, 0x1e000
	s_cmpk_lt_u32 s20, 0x100
	global_load_lds_dwordx4 v[2:3], off
	v_lshlrev_b32_e32 v2, 14, v10
	v_and_b32_e32 v2, 0xffff8000, v2
	v_lshl_add_u32 v2, v11, 11, v2
	v_and_b32_e32 v3, 1, v10
	v_lshl_or_b32 v2, v3, 6, v2
	v_lshl_add_u32 v136, v12, 1, v2
	v_lshlrev_b32_e32 v2, 14, v14
	v_and_b32_e32 v2, 0xffff8000, v2
	s_waitcnt vmcnt(6)
	v_lshl_add_u32 v2, v13, 11, v2
	v_and_b32_e32 v3, 1, v14
	v_lshl_or_b32 v2, v3, 6, v2
	v_readlane_b32 s26, v255, 63
	s_cselect_b64 s[44:45], -1, 0
	s_waitcnt vmcnt(0)
	v_or_b32_e32 v147, s21, v18
	v_mov_b32_e32 v137, v1
	v_lshl_add_u32 v138, v15, 1, v2
	v_mov_b32_e32 v139, v1
	s_mov_b32 s65, 0
	v_add_u32_e32 v149, 0, v19
	v_readlane_b32 s20, v255, 56
	s_mov_b32 s21, s26
	s_barrier
	v_readlane_b32 s27, v254, 0
	v_lshl_add_u32 v238, s21, 8, v141
	v_mov_b32_e32 v239, 0
	v_lshl_add_u64 v[238:239], v[238:239], 2, s[4:5]
	global_load_dword v240, v[238:239], off
	global_load_dword v241, v[238:239], off offset:64
	global_load_dword v242, v[238:239], off offset:128
	global_load_dword v243, v[238:239], off offset:192
	global_load_dword v244, v[238:239], off offset:512
	global_load_dword v245, v[238:239], off offset:576
	global_load_dword v246, v[238:239], off offset:640
	global_load_dword v247, v[238:239], off offset:704
	s_mov_b32 s98, 0x00ff00ff
	s_mov_b32 s99, 0x00ff00ff
	s_mov_b32 s100, 0x10000
	s_mov_b32 s101, 0
	s_branch .LBB0_554

.LBB0_561:
	s_add_i32 s66, 0, 0x10000
	v_add_u32_e32 v140, s66, v145
	s_add_i32 s68, 0, 0x14000
	ds_read_b128 v[150:153], v140
	ds_read_b128 v[154:157], v140 offset:1024
	ds_read_b128 v[158:161], v140 offset:2048
	ds_read_b128 v[162:165], v140 offset:3072
	v_add_u32_e32 v140, s68, v145
	ds_read_b128 v[166:169], v140
	ds_read_b128 v[170:173], v140 offset:1024
	ds_read_b128 v[174:177], v140 offset:2048
	ds_read_b128 v[178:181], v140 offset:3072
	v_lshl_add_u64 v[142:143], s[12:13], 0, v[138:139]
	s_add_i32 m0, s59, 0xc000
	ds_read_b128 v[182:185], v149
	ds_read_b128 v[186:189], v149 offset:1024
	ds_read_b128 v[190:193], v149 offset:2048
	ds_read_b128 v[202:205], v149 offset:3072
	ds_read_b128 v[206:209], v149 offset:4096
	ds_read_b128 v[210:213], v149 offset:5120
	ds_read_b128 v[214:217], v149 offset:6144
	ds_read_b128 v[218:221], v149 offset:7168
	s_add_u32 s14, s12, 0xfffc0080
	s_addc_u32 s15, s13, -1
	s_cmp_eq_u32 s49, 12
	s_cselect_b32 s55, s28, s15
	s_cselect_b32 s54, s29, s14
	s_cselect_b32 s15, s33, s47
	s_cselect_b32 s14, s36, s37
	global_load_lds_dwordx4 v[142:143], off
	v_lshl_add_u64 v[142:143], s[12:13], 0, v[136:137]
	s_add_i32 m0, s59, 0xe000
	s_nop 0
	global_load_lds_dwordx4 v[142:143], off
	s_waitcnt vmcnt(8)
	s_waitcnt lgkmcnt(0)
	s_setprio 1
	s_barrier
	v_mfma_f32_16x16x32_bf16 v[126:129], v[150:153], v[182:185], v[126:129]
	v_mfma_f32_16x16x32_bf16 v[122:125], v[158:161], v[182:185], v[122:125]
	v_mfma_f32_16x16x32_bf16 v[110:113], v[150:153], v[190:193], v[110:113]
	v_mfma_f32_16x16x32_bf16 v[106:109], v[158:161], v[190:193], v[106:109]
	v_mfma_f32_16x16x32_bf16 v[94:97], v[150:153], v[206:209], v[94:97]
	v_mfma_f32_16x16x32_bf16 v[90:93], v[158:161], v[206:209], v[90:93]
	v_mfma_f32_16x16x32_bf16 v[78:81], v[150:153], v[214:217], v[78:81]
	v_mfma_f32_16x16x32_bf16 v[74:77], v[158:161], v[214:217], v[74:77]
	v_mfma_f32_16x16x32_bf16 v[126:129], v[154:157], v[186:189], v[126:129]
	v_mfma_f32_16x16x32_bf16 v[122:125], v[162:165], v[186:189], v[122:125]
	v_mfma_f32_16x16x32_bf16 v[110:113], v[154:157], v[202:205], v[110:113]
	v_mfma_f32_16x16x32_bf16 v[106:109], v[162:165], v[202:205], v[106:109]
	v_mfma_f32_16x16x32_bf16 v[94:97], v[154:157], v[210:213], v[94:97]
	v_mfma_f32_16x16x32_bf16 v[90:93], v[162:165], v[210:213], v[90:93]
	v_mfma_f32_16x16x32_bf16 v[78:81], v[154:157], v[218:221], v[78:81]
	v_mfma_f32_16x16x32_bf16 v[74:77], v[162:165], v[218:221], v[74:77]
	v_mfma_f32_16x16x32_bf16 v[118:121], v[166:169], v[182:185], v[118:121]
	v_mfma_f32_16x16x32_bf16 v[114:117], v[174:177], v[182:185], v[114:117]
	v_mfma_f32_16x16x32_bf16 v[102:105], v[166:169], v[190:193], v[102:105]
	v_mfma_f32_16x16x32_bf16 v[98:101], v[174:177], v[190:193], v[98:101]
	v_mfma_f32_16x16x32_bf16 v[86:89], v[166:169], v[206:209], v[86:89]
	v_mfma_f32_16x16x32_bf16 v[82:85], v[174:177], v[206:209], v[82:85]
	v_mfma_f32_16x16x32_bf16 v[70:73], v[166:169], v[214:217], v[70:73]
	v_mfma_f32_16x16x32_bf16 v[66:69], v[174:177], v[214:217], v[66:69]
	v_mfma_f32_16x16x32_bf16 v[118:121], v[170:173], v[186:189], v[118:121]
	v_mfma_f32_16x16x32_bf16 v[114:117], v[178:181], v[186:189], v[114:117]
	v_mfma_f32_16x16x32_bf16 v[102:105], v[170:173], v[202:205], v[102:105]
	v_mfma_f32_16x16x32_bf16 v[98:101], v[178:181], v[202:205], v[98:101]
	v_mfma_f32_16x16x32_bf16 v[86:89], v[170:173], v[210:213], v[86:89]
	v_mfma_f32_16x16x32_bf16 v[82:85], v[178:181], v[210:213], v[82:85]
	v_mfma_f32_16x16x32_bf16 v[70:73], v[170:173], v[218:221], v[70:73]
	v_mfma_f32_16x16x32_bf16 v[66:69], v[178:181], v[218:221], v[66:69]
	s_barrier
	s_setprio 0
	s_add_i32 s66, s66, s58
	v_lshl_add_u64 v[142:143], s[14:15], 0, v[0:1]
	s_mov_b32 m0, s66
	ds_read_b128 v[182:185], v149 offset:16384
	ds_read_b128 v[186:189], v149 offset:17408
	ds_read_b128 v[190:193], v149 offset:18432
	ds_read_b128 v[202:205], v149 offset:19456
	ds_read_b128 v[206:209], v149 offset:20480
	ds_read_b128 v[210:213], v149 offset:21504
	ds_read_b128 v[214:217], v149 offset:22528
	ds_read_b128 v[218:221], v149 offset:23552
	global_load_lds_dwordx4 v[142:143], off
	s_add_i32 m0, s66, 0x2000
	s_add_u32 s66, s14, 0x10000
	v_lshl_add_u64 v[222:223], s[14:15], 0, v[130:131]
	s_addc_u32 s67, s15, 0
	s_add_i32 s68, s68, s58
	global_load_lds_dwordx4 v[222:223], off
	v_lshl_add_u64 v[232:233], s[66:67], 0, v[0:1]
	s_mov_b32 m0, s68
	v_lshl_add_u64 v[234:235], s[54:55], 0, v[132:133]
	global_load_lds_dwordx4 v[232:233], off
	v_lshl_add_u64 v[232:233], s[66:67], 0, v[130:131]
	s_add_i32 m0, s68, 0x2000
	s_nop 0
	global_load_lds_dwordx4 v[232:233], off
	v_lshl_add_u64 v[232:233], s[54:55], 0, v[134:135]
	s_mov_b32 m0, s59
	s_nop 0
	global_load_lds_dwordx4 v[232:233], off
	s_mov_b32 m0, s60
	s_nop 0
	global_load_lds_dwordx4 v[234:235], off
	s_waitcnt vmcnt(8)
	s_waitcnt lgkmcnt(0)
	s_setprio 1
	s_barrier
	v_mfma_f32_16x16x32_bf16 v[62:65], v[150:153], v[182:185], v[62:65]
	v_mfma_f32_16x16x32_bf16 v[58:61], v[158:161], v[182:185], v[58:61]
	v_mfma_f32_16x16x32_bf16 v[46:49], v[150:153], v[190:193], v[46:49]
	v_mfma_f32_16x16x32_bf16 v[42:45], v[158:161], v[190:193], v[42:45]
	v_mfma_f32_16x16x32_bf16 v[30:33], v[150:153], v[206:209], v[30:33]
	v_mfma_f32_16x16x32_bf16 v[26:29], v[158:161], v[206:209], v[26:29]
	v_mfma_f32_16x16x32_bf16 v[14:17], v[150:153], v[214:217], v[14:17]
	v_mfma_f32_16x16x32_bf16 v[10:13], v[158:161], v[214:217], v[10:13]
	v_mfma_f32_16x16x32_bf16 v[62:65], v[154:157], v[186:189], v[62:65]
	v_mfma_f32_16x16x32_bf16 v[58:61], v[162:165], v[186:189], v[58:61]
	v_mfma_f32_16x16x32_bf16 v[46:49], v[154:157], v[202:205], v[46:49]
	v_mfma_f32_16x16x32_bf16 v[42:45], v[162:165], v[202:205], v[42:45]
	v_mfma_f32_16x16x32_bf16 v[30:33], v[154:157], v[210:213], v[30:33]
	v_mfma_f32_16x16x32_bf16 v[26:29], v[162:165], v[210:213], v[26:29]
	v_mfma_f32_16x16x32_bf16 v[14:17], v[154:157], v[218:221], v[14:17]
	v_mfma_f32_16x16x32_bf16 v[10:13], v[162:165], v[218:221], v[10:13]
	v_mfma_f32_16x16x32_bf16 v[54:57], v[166:169], v[182:185], v[54:57]
	v_mfma_f32_16x16x32_bf16 v[50:53], v[174:177], v[182:185], v[50:53]
	v_mfma_f32_16x16x32_bf16 v[38:41], v[166:169], v[190:193], v[38:41]
	v_mfma_f32_16x16x32_bf16 v[34:37], v[174:177], v[190:193], v[34:37]
	v_mfma_f32_16x16x32_bf16 v[22:25], v[166:169], v[206:209], v[22:25]
	v_mfma_f32_16x16x32_bf16 v[18:21], v[174:177], v[206:209], v[18:21]
	v_mfma_f32_16x16x32_bf16 v[6:9], v[166:169], v[214:217], v[6:9]
	v_mfma_f32_16x16x32_bf16 v[2:5], v[174:177], v[214:217], v[2:5]
	v_mfma_f32_16x16x32_bf16 v[54:57], v[170:173], v[186:189], v[54:57]
	v_mfma_f32_16x16x32_bf16 v[50:53], v[178:181], v[186:189], v[50:53]
	v_mfma_f32_16x16x32_bf16 v[38:41], v[170:173], v[202:205], v[38:41]
	v_mfma_f32_16x16x32_bf16 v[34:37], v[178:181], v[202:205], v[34:37]
	v_mfma_f32_16x16x32_bf16 v[22:25], v[170:173], v[210:213], v[22:25]
	v_mfma_f32_16x16x32_bf16 v[18:21], v[178:181], v[210:213], v[18:21]
	v_mfma_f32_16x16x32_bf16 v[6:9], v[170:173], v[218:221], v[6:9]
	v_mfma_f32_16x16x32_bf16 v[2:5], v[178:181], v[218:221], v[2:5]
	s_barrier
	s_setprio 0
	s_add_i32 s66, 0, 0x18000
	v_add_u32_e32 v140, s66, v145
	s_add_i32 s67, 0, 0x1c000
	ds_read_b128 v[150:153], v140
	ds_read_b128 v[154:157], v140 offset:1024
	ds_read_b128 v[158:161], v140 offset:2048
	ds_read_b128 v[162:165], v140 offset:3072
	v_add_u32_e32 v140, s67, v145
	ds_read_b128 v[166:169], v140
	ds_read_b128 v[170:173], v140 offset:1024
	ds_read_b128 v[174:177], v140 offset:2048
	ds_read_b128 v[178:181], v140 offset:3072
	s_add_u32 s54, s54, 0x40000
	s_addc_u32 s55, s55, 0
	s_mov_b32 m0, s61
	v_lshl_add_u64 v[236:237], s[54:55], 0, v[134:135]
	ds_read_b128 v[182:185], v149 offset:32768
	ds_read_b128 v[186:189], v149 offset:33792
	ds_read_b128 v[190:193], v149 offset:34816
	ds_read_b128 v[202:205], v149 offset:35840
	ds_read_b128 v[206:209], v149 offset:36864
	ds_read_b128 v[210:213], v149 offset:37888
	ds_read_b128 v[214:217], v149 offset:38912
	ds_read_b128 v[218:221], v149 offset:39936
	global_load_lds_dwordx4 v[236:237], off
	v_lshl_add_u64 v[236:237], s[54:55], 0, v[132:133]
	s_mov_b32 m0, s62
	s_nop 0
	global_load_lds_dwordx4 v[236:237], off
	s_waitcnt vmcnt(8)
	s_waitcnt lgkmcnt(0)
	s_setprio 1
	s_barrier
	v_mfma_f32_16x16x32_bf16 v[126:129], v[150:153], v[182:185], v[126:129]
	v_mfma_f32_16x16x32_bf16 v[122:125], v[158:161], v[182:185], v[122:125]
	v_mfma_f32_16x16x32_bf16 v[110:113], v[150:153], v[190:193], v[110:113]
	v_mfma_f32_16x16x32_bf16 v[106:109], v[158:161], v[190:193], v[106:109]
	v_mfma_f32_16x16x32_bf16 v[94:97], v[150:153], v[206:209], v[94:97]
	v_mfma_f32_16x16x32_bf16 v[90:93], v[158:161], v[206:209], v[90:93]
	v_mfma_f32_16x16x32_bf16 v[78:81], v[150:153], v[214:217], v[78:81]
	v_mfma_f32_16x16x32_bf16 v[74:77], v[158:161], v[214:217], v[74:77]
	v_mfma_f32_16x16x32_bf16 v[126:129], v[154:157], v[186:189], v[126:129]
	v_mfma_f32_16x16x32_bf16 v[122:125], v[162:165], v[186:189], v[122:125]
	v_mfma_f32_16x16x32_bf16 v[110:113], v[154:157], v[202:205], v[110:113]
	v_mfma_f32_16x16x32_bf16 v[106:109], v[162:165], v[202:205], v[106:109]
	v_mfma_f32_16x16x32_bf16 v[94:97], v[154:157], v[210:213], v[94:97]
	v_mfma_f32_16x16x32_bf16 v[90:93], v[162:165], v[210:213], v[90:93]
	v_mfma_f32_16x16x32_bf16 v[78:81], v[154:157], v[218:221], v[78:81]
	v_mfma_f32_16x16x32_bf16 v[74:77], v[162:165], v[218:221], v[74:77]
	v_mfma_f32_16x16x32_bf16 v[118:121], v[166:169], v[182:185], v[118:121]
	v_mfma_f32_16x16x32_bf16 v[114:117], v[174:177], v[182:185], v[114:117]
	v_mfma_f32_16x16x32_bf16 v[102:105], v[166:169], v[190:193], v[102:105]
	v_mfma_f32_16x16x32_bf16 v[98:101], v[174:177], v[190:193], v[98:101]
	v_mfma_f32_16x16x32_bf16 v[86:89], v[166:169], v[206:209], v[86:89]
	v_mfma_f32_16x16x32_bf16 v[82:85], v[174:177], v[206:209], v[82:85]
	v_mfma_f32_16x16x32_bf16 v[70:73], v[166:169], v[214:217], v[70:73]
	v_mfma_f32_16x16x32_bf16 v[66:69], v[174:177], v[214:217], v[66:69]
	v_mfma_f32_16x16x32_bf16 v[118:121], v[170:173], v[186:189], v[118:121]
	v_mfma_f32_16x16x32_bf16 v[114:117], v[178:181], v[186:189], v[114:117]
	v_mfma_f32_16x16x32_bf16 v[102:105], v[170:173], v[202:205], v[102:105]
	v_mfma_f32_16x16x32_bf16 v[98:101], v[178:181], v[202:205], v[98:101]
	v_mfma_f32_16x16x32_bf16 v[86:89], v[170:173], v[210:213], v[86:89]
	v_mfma_f32_16x16x32_bf16 v[82:85], v[178:181], v[210:213], v[82:85]
	v_mfma_f32_16x16x32_bf16 v[70:73], v[170:173], v[218:221], v[70:73]
	v_mfma_f32_16x16x32_bf16 v[66:69], v[178:181], v[218:221], v[66:69]
	s_barrier
	s_setprio 0
	s_add_i32 s54, s66, s58
	v_lshl_add_u64 v[142:143], v[142:143], 0, s[10:11]
	s_mov_b32 m0, s54
	ds_read_b128 v[182:185], v149 offset:49152
	ds_read_b128 v[186:189], v149 offset:50176
	ds_read_b128 v[190:193], v149 offset:51200
	ds_read_b128 v[202:205], v149 offset:52224
	ds_read_b128 v[206:209], v149 offset:53248
	ds_read_b128 v[210:213], v149 offset:54272
	ds_read_b128 v[214:217], v149 offset:55296
	ds_read_b128 v[218:221], v149 offset:56320
	s_add_i32 s49, s49, 2
	s_add_u32 s37, s37, 0x100
	s_addc_u32 s47, s47, 0
	s_add_u32 s12, s12, 0x100
	s_addc_u32 s13, s13, 0
	global_load_lds_dwordx4 v[142:143], off
	s_add_i32 m0, s54, 0x2000
	s_add_u32 s14, s14, 0x10080
	v_lshl_add_u64 v[142:143], v[222:223], 0, s[10:11]
	s_addc_u32 s15, s15, 0
	s_add_i32 s54, s67, s58
	global_load_lds_dwordx4 v[142:143], off
	v_lshl_add_u64 v[142:143], s[14:15], 0, v[0:1]
	s_mov_b32 m0, s54
	s_nop 0
	global_load_lds_dwordx4 v[142:143], off
	v_lshl_add_u64 v[142:143], s[14:15], 0, v[130:131]
	s_add_i32 m0, s54, 0x2000
	s_nop 0
	global_load_lds_dwordx4 v[142:143], off
	v_lshl_add_u64 v[142:143], v[232:233], 0, s[10:11]
	s_mov_b32 m0, s63
	s_nop 0
	global_load_lds_dwordx4 v[142:143], off
	v_lshl_add_u64 v[142:143], v[234:235], 0, s[10:11]
	s_mov_b32 m0, s64
	s_nop 0
	global_load_lds_dwordx4 v[142:143], off
	s_waitcnt vmcnt(8)
	s_waitcnt lgkmcnt(0)
	s_setprio 1
	s_barrier
	v_mfma_f32_16x16x32_bf16 v[62:65], v[150:153], v[182:185], v[62:65]
	v_mfma_f32_16x16x32_bf16 v[58:61], v[158:161], v[182:185], v[58:61]
	v_mfma_f32_16x16x32_bf16 v[46:49], v[150:153], v[190:193], v[46:49]
	v_mfma_f32_16x16x32_bf16 v[42:45], v[158:161], v[190:193], v[42:45]
	v_mfma_f32_16x16x32_bf16 v[30:33], v[150:153], v[206:209], v[30:33]
	v_mfma_f32_16x16x32_bf16 v[26:29], v[158:161], v[206:209], v[26:29]
	v_mfma_f32_16x16x32_bf16 v[14:17], v[150:153], v[214:217], v[14:17]
	v_mfma_f32_16x16x32_bf16 v[10:13], v[158:161], v[214:217], v[10:13]
	v_mfma_f32_16x16x32_bf16 v[62:65], v[154:157], v[186:189], v[62:65]
	v_mfma_f32_16x16x32_bf16 v[58:61], v[162:165], v[186:189], v[58:61]
	v_mfma_f32_16x16x32_bf16 v[46:49], v[154:157], v[202:205], v[46:49]
	v_mfma_f32_16x16x32_bf16 v[42:45], v[162:165], v[202:205], v[42:45]
	v_mfma_f32_16x16x32_bf16 v[30:33], v[154:157], v[210:213], v[30:33]
	v_mfma_f32_16x16x32_bf16 v[26:29], v[162:165], v[210:213], v[26:29]
	v_mfma_f32_16x16x32_bf16 v[14:17], v[154:157], v[218:221], v[14:17]
	v_mfma_f32_16x16x32_bf16 v[10:13], v[162:165], v[218:221], v[10:13]
	v_mfma_f32_16x16x32_bf16 v[54:57], v[166:169], v[182:185], v[54:57]
	v_mfma_f32_16x16x32_bf16 v[50:53], v[174:177], v[182:185], v[50:53]
	v_mfma_f32_16x16x32_bf16 v[38:41], v[166:169], v[190:193], v[38:41]
	v_mfma_f32_16x16x32_bf16 v[34:37], v[174:177], v[190:193], v[34:37]
	v_mfma_f32_16x16x32_bf16 v[22:25], v[166:169], v[206:209], v[22:25]
	v_mfma_f32_16x16x32_bf16 v[18:21], v[174:177], v[206:209], v[18:21]
	v_mfma_f32_16x16x32_bf16 v[6:9], v[166:169], v[214:217], v[6:9]
	v_mfma_f32_16x16x32_bf16 v[2:5], v[174:177], v[214:217], v[2:5]
	v_mfma_f32_16x16x32_bf16 v[54:57], v[170:173], v[186:189], v[54:57]
	v_mfma_f32_16x16x32_bf16 v[50:53], v[178:181], v[186:189], v[50:53]
	v_mfma_f32_16x16x32_bf16 v[38:41], v[170:173], v[202:205], v[38:41]
	v_mfma_f32_16x16x32_bf16 v[34:37], v[178:181], v[202:205], v[34:37]
	v_mfma_f32_16x16x32_bf16 v[22:25], v[170:173], v[210:213], v[22:25]
	v_mfma_f32_16x16x32_bf16 v[18:21], v[178:181], v[210:213], v[18:21]
	v_mfma_f32_16x16x32_bf16 v[6:9], v[170:173], v[218:221], v[6:9]
	v_mfma_f32_16x16x32_bf16 v[2:5], v[178:181], v[218:221], v[2:5]
	s_barrier
	s_setprio 0
	s_cmp_gt_u32 s49, 13
	s_cbranch_scc0 .LBB0_561
	s_and_b64 vcc, exec, s[44:45]
	s_cbranch_vccz .LBB0_564
	s_barrier
.LBB0_564:
	v_lshl_add_u32 v150, s21, 8, v141
	v_ashrrev_i32_e32 v151, 31, v150
	v_and_b32_e32 v249, 8, v228
	v_sub_u32_e32 v150, v150, v249
	s_and_b64 s[12:13], s[40:41], exec
	s_cselect_b32 s12, s48, s21
	v_lshl_add_u32 v238, s12, 8, v141
	v_mov_b32_e32 v239, 0
	v_lshl_add_u64 v[238:239], v[238:239], 2, s[4:5]
	s_mov_b64 s[12:13], 0x100000
	s_waitcnt vmcnt(8)
	v_fmamk_f32 v140, v240, 0x3a800000, v225
	v_rsq_f32_e32 v160, v140
	v_fmamk_f32 v144, v241, 0x3a800000, v225
	v_rsq_f32_e32 v158, v144
	v_fmamk_f32 v153, v244, 0x3a800000, v225
	v_pk_mul_f32 v[122:123], v[122:123], v[160:161] op_sel_hi:[1,0]
	v_pk_mul_f32 v[126:127], v[126:127], v[160:161] op_sel_hi:[1,0]
	v_pk_mul_f32 v[124:125], v[124:125], v[160:161] op_sel_hi:[1,0]
	v_max_f32_e32 v122, 0, v122
	v_pk_mul_f32 v[128:129], v[128:129], v[160:161] op_sel_hi:[1,0]
	v_max_f32_e32 v123, 0, v123
	v_max_f32_e32 v124, 0, v124
	v_max_f32_e32 v126, 0, v126
	v_max_f32_e32 v125, 0, v125
	v_pk_mul_f32 v[114:115], v[114:115], v[160:161] op_sel_hi:[1,0]
	v_mul_f32_e32 v126, v126, v126
	v_mul_f32_e32 v125, v125, v125
	v_pk_mul_f32 v[118:119], v[118:119], v[160:161] op_sel_hi:[1,0]
	v_pk_mul_f32 v[116:117], v[116:117], v[160:161] op_sel_hi:[1,0]
	v_max_f32_e32 v114, 0, v114
	v_pk_mul_f32 v[120:121], v[120:121], v[160:161] op_sel_hi:[1,0]
	v_max_f32_e32 v115, 0, v115
	v_max_f32_e32 v116, 0, v116
	v_max_f32_e32 v118, 0, v118
	v_max_f32_e32 v117, 0, v117
	v_mul_f32_e32 v118, v118, v118
	v_mul_f32_e32 v117, v117, v117
	v_pk_mul_f32 v[106:107], v[106:107], v[158:159] op_sel_hi:[1,0]
	v_pk_mul_f32 v[110:111], v[110:111], v[158:159] op_sel_hi:[1,0]
	v_pk_mul_f32 v[108:109], v[108:109], v[158:159] op_sel_hi:[1,0]
	v_max_f32_e32 v106, 0, v106
	v_pk_mul_f32 v[112:113], v[112:113], v[158:159] op_sel_hi:[1,0]
	v_max_f32_e32 v107, 0, v107
	v_max_f32_e32 v108, 0, v108
	v_fmamk_f32 v146, v242, 0x3a800000, v225
	v_max_f32_e32 v110, 0, v110
	v_max_f32_e32 v109, 0, v109
	v_pk_mul_f32 v[98:99], v[98:99], v[158:159] op_sel_hi:[1,0]
	v_rsq_f32_e32 v154, v146
	v_mul_f32_e32 v110, v110, v110
	v_mul_f32_e32 v109, v109, v109
	v_pk_mul_f32 v[102:103], v[102:103], v[158:159] op_sel_hi:[1,0]
	v_pk_mul_f32 v[100:101], v[100:101], v[158:159] op_sel_hi:[1,0]
	v_max_f32_e32 v98, 0, v98
	v_pk_mul_f32 v[104:105], v[104:105], v[158:159] op_sel_hi:[1,0]
	v_max_f32_e32 v99, 0, v99
	v_max_f32_e32 v100, 0, v100
	v_max_f32_e32 v102, 0, v102
	v_max_f32_e32 v101, 0, v101
	v_mul_f32_e32 v102, v102, v102
	v_mul_f32_e32 v101, v101, v101
	v_fmamk_f32 v148, v243, 0x3a800000, v225
	v_fmamk_f32 v155, v245, 0x3a800000, v225
	v_pk_mul_f32 v[90:91], v[90:91], v[154:155] op_sel_hi:[1,0]
	v_pk_mul_f32 v[94:95], v[94:95], v[154:155] op_sel_hi:[1,0]
	v_pk_mul_f32 v[92:93], v[92:93], v[154:155] op_sel_hi:[1,0]
	v_max_f32_e32 v90, 0, v90
	v_pk_mul_f32 v[96:97], v[96:97], v[154:155] op_sel_hi:[1,0]
	v_max_f32_e32 v91, 0, v91
	v_max_f32_e32 v92, 0, v92
	v_max_f32_e32 v94, 0, v94
	v_max_f32_e32 v93, 0, v93
	v_pk_mul_f32 v[82:83], v[82:83], v[154:155] op_sel_hi:[1,0]
	v_mul_f32_e32 v94, v94, v94
	v_mul_f32_e32 v93, v93, v93
	v_pk_mul_f32 v[86:87], v[86:87], v[154:155] op_sel_hi:[1,0]
	v_pk_mul_f32 v[84:85], v[84:85], v[154:155] op_sel_hi:[1,0]
	v_max_f32_e32 v82, 0, v82
	v_pk_mul_f32 v[88:89], v[88:89], v[154:155] op_sel_hi:[1,0]
	v_max_f32_e32 v83, 0, v83
	v_max_f32_e32 v84, 0, v84
	v_max_f32_e32 v86, 0, v86
	v_max_f32_e32 v85, 0, v85
	v_mul_f32_e32 v86, v86, v86
	v_mul_f32_e32 v85, v85, v85
	v_rsq_f32_e32 v146, v155
	v_fmamk_f32 v156, v246, 0x3a800000, v225
	v_rsq_f32_e32 v144, v156
	v_fmamk_f32 v142, v247, 0x3a800000, v225
	v_rsq_f32_e32 v140, v142
	global_load_dword v240, v[238:239], off
	global_load_dword v241, v[238:239], off offset:64
	global_load_dword v242, v[238:239], off offset:128
	global_load_dword v243, v[238:239], off offset:192
	global_load_dword v244, v[238:239], off offset:512
	global_load_dword v245, v[238:239], off offset:576
	global_load_dword v246, v[238:239], off offset:640
	global_load_dword v247, v[238:239], off offset:704
	v_lshl_or_b32 v142, s20, 8, v147
	v_lshl_add_u32 v142, v249, 2, v142
	v_bfe_u32 v250, v224, 6, 2
	v_lshl_add_u32 v142, v250, 5, v142
	v_ashrrev_i32_e32 v143, 31, v142
	v_lshlrev_b64 v[156:157], 13, v[150:151]
	v_mul_f32_e32 v151, v122, v122
	v_max_f32_e32 v122, 0, v127
	v_lshl_add_u64 v[162:163], s[42:43], 0, v[156:157]
	v_lshlrev_b64 v[156:157], 1, v[142:143]
	v_mul_f32_e32 v122, v122, v122
	v_mul_f32_e32 v127, v123, v123
	v_max_f32_e32 v123, 0, v128
	v_mul_f32_e32 v128, v124, v124
	v_max_f32_e32 v124, 0, v129
	v_lshl_add_u64 v[142:143], v[162:163], 0, v[156:157]
	v_mul_f32_e32 v123, v123, v123
	v_mul_f32_e32 v124, v124, v124
	v_cvt_pk_bf16_f32 v122, v126, v122
	v_cvt_pk_bf16_f32 v123, v123, v124
	v_cvt_pk_bf16_f32 v124, v151, v127
	v_cvt_pk_bf16_f32 v125, v128, v125
	v_mov_b32_e32 v248, v122
	v_mov_b32_e32 v249, v123
	v_mov_b32_e32 v250, v124
	v_mov_b32_e32 v251, v125
	v_rsq_f32_e32 v152, v148
	v_rsq_f32_e32 v148, v153
	v_mul_f32_e32 v122, v114, v114
	v_max_f32_e32 v114, 0, v119
	v_mul_f32_e32 v114, v114, v114
	v_mul_f32_e32 v119, v115, v115
	v_max_f32_e32 v115, 0, v120
	v_mul_f32_e32 v120, v116, v116
	v_max_f32_e32 v116, 0, v121
	v_mul_f32_e32 v115, v115, v115
	v_mul_f32_e32 v116, v116, v116
	v_cvt_pk_bf16_f32 v114, v118, v114
	v_cvt_pk_bf16_f32 v115, v115, v116
	v_cvt_pk_bf16_f32 v116, v122, v119
	v_cvt_pk_bf16_f32 v117, v120, v117
	v_mov_b32_dpp v252, v248 row_ror:8 row_mask:0xf bank_mask:0xf
	v_mov_b32_dpp v226, v114 row_ror:8 row_mask:0xf bank_mask:0xf
	v_cndmask_b32_e64 v114, v114, v252, s[98:99]
	v_cndmask_b32_e64 v248, v226, v248, s[98:99]
	v_mov_b32_dpp v252, v249 row_ror:8 row_mask:0xf bank_mask:0xf
	v_mov_b32_dpp v226, v115 row_ror:8 row_mask:0xf bank_mask:0xf
	v_cndmask_b32_e64 v115, v115, v252, s[98:99]
	v_cndmask_b32_e64 v249, v226, v249, s[98:99]
	v_mov_b32_dpp v252, v250 row_ror:8 row_mask:0xf bank_mask:0xf
	v_mov_b32_dpp v226, v116 row_ror:8 row_mask:0xf bank_mask:0xf
	v_cndmask_b32_e64 v116, v116, v252, s[98:99]
	v_cndmask_b32_e64 v250, v226, v250, s[98:99]
	v_mov_b32_dpp v252, v251 row_ror:8 row_mask:0xf bank_mask:0xf
	v_mov_b32_dpp v226, v117 row_ror:8 row_mask:0xf bank_mask:0xf
	v_cndmask_b32_e64 v117, v117, v252, s[98:99]
	v_cndmask_b32_e64 v251, v226, v251, s[98:99]
	v_lshl_add_u64 v[226:227], v[142:143], 0, s[100:101]
	flat_store_dwordx4 v[142:143], v[248:251] nt
	flat_store_dwordx4 v[226:227], v[114:117] nt
	v_pk_mul_f32 v[74:75], v[74:75], v[152:153] op_sel_hi:[1,0]
	v_pk_mul_f32 v[78:79], v[78:79], v[152:153] op_sel_hi:[1,0]
	v_or_b32_e32 v114, 16, v150
	v_ashrrev_i32_e32 v115, 31, v114
	v_lshlrev_b64 v[114:115], 13, v[114:115]
	v_mul_f32_e32 v116, v106, v106
	v_max_f32_e32 v106, 0, v111
	v_lshl_add_u64 v[114:115], s[42:43], 0, v[114:115]
	v_mul_f32_e32 v106, v106, v106
	v_mul_f32_e32 v111, v107, v107
	v_max_f32_e32 v107, 0, v112
	v_mul_f32_e32 v112, v108, v108
	v_max_f32_e32 v108, 0, v113
	v_lshl_add_u64 v[114:115], v[114:115], 0, v[156:157]
	v_mul_f32_e32 v107, v107, v107
	v_mul_f32_e32 v108, v108, v108
	v_cvt_pk_bf16_f32 v106, v110, v106
	v_cvt_pk_bf16_f32 v107, v107, v108
	v_cvt_pk_bf16_f32 v108, v116, v111
	v_cvt_pk_bf16_f32 v109, v112, v109
	v_mov_b32_e32 v248, v106
	v_mov_b32_e32 v249, v107
	v_mov_b32_e32 v250, v108
	v_mov_b32_e32 v251, v109
	v_pk_mul_f32 v[76:77], v[76:77], v[152:153] op_sel_hi:[1,0]
	v_max_f32_e32 v74, 0, v74
	v_mul_f32_e32 v106, v98, v98
	v_max_f32_e32 v98, 0, v103
	v_mul_f32_e32 v98, v98, v98
	v_mul_f32_e32 v103, v99, v99
	v_max_f32_e32 v99, 0, v104
	v_mul_f32_e32 v104, v100, v100
	v_max_f32_e32 v100, 0, v105
	v_mul_f32_e32 v99, v99, v99
	v_mul_f32_e32 v100, v100, v100
	v_cvt_pk_bf16_f32 v98, v102, v98
	v_cvt_pk_bf16_f32 v99, v99, v100
	v_cvt_pk_bf16_f32 v100, v106, v103
	v_cvt_pk_bf16_f32 v101, v104, v101
	v_mov_b32_dpp v252, v248 row_ror:8 row_mask:0xf bank_mask:0xf
	v_mov_b32_dpp v226, v98 row_ror:8 row_mask:0xf bank_mask:0xf
	v_cndmask_b32_e64 v98, v98, v252, s[98:99]
	v_cndmask_b32_e64 v248, v226, v248, s[98:99]
	v_mov_b32_dpp v252, v249 row_ror:8 row_mask:0xf bank_mask:0xf
	v_mov_b32_dpp v226, v99 row_ror:8 row_mask:0xf bank_mask:0xf
	v_cndmask_b32_e64 v99, v99, v252, s[98:99]
	v_cndmask_b32_e64 v249, v226, v249, s[98:99]
	v_mov_b32_dpp v252, v250 row_ror:8 row_mask:0xf bank_mask:0xf
	v_mov_b32_dpp v226, v100 row_ror:8 row_mask:0xf bank_mask:0xf
	v_cndmask_b32_e64 v100, v100, v252, s[98:99]
	v_cndmask_b32_e64 v250, v226, v250, s[98:99]
	v_mov_b32_dpp v252, v251 row_ror:8 row_mask:0xf bank_mask:0xf
	v_mov_b32_dpp v226, v101 row_ror:8 row_mask:0xf bank_mask:0xf
	v_cndmask_b32_e64 v101, v101, v252, s[98:99]
	v_cndmask_b32_e64 v251, v226, v251, s[98:99]
	v_lshl_add_u64 v[226:227], v[114:115], 0, s[100:101]
	flat_store_dwordx4 v[114:115], v[248:251] nt
	flat_store_dwordx4 v[226:227], v[98:101] nt
	v_pk_mul_f32 v[80:81], v[80:81], v[152:153] op_sel_hi:[1,0]
	v_max_f32_e32 v75, 0, v75
	v_or_b32_e32 v98, 32, v150
	v_ashrrev_i32_e32 v99, 31, v98
	v_lshlrev_b64 v[98:99], 13, v[98:99]
	v_mul_f32_e32 v100, v90, v90
	v_max_f32_e32 v90, 0, v95
	v_lshl_add_u64 v[98:99], s[42:43], 0, v[98:99]
	v_mul_f32_e32 v90, v90, v90
	v_mul_f32_e32 v95, v91, v91
	v_max_f32_e32 v91, 0, v96
	v_mul_f32_e32 v96, v92, v92
	v_max_f32_e32 v92, 0, v97
	v_lshl_add_u64 v[98:99], v[98:99], 0, v[156:157]
	v_mul_f32_e32 v91, v91, v91
	v_mul_f32_e32 v92, v92, v92
	v_cvt_pk_bf16_f32 v90, v94, v90
	v_cvt_pk_bf16_f32 v91, v91, v92
	v_cvt_pk_bf16_f32 v92, v100, v95
	v_cvt_pk_bf16_f32 v93, v96, v93
	v_mov_b32_e32 v248, v90
	v_mov_b32_e32 v249, v91
	v_mov_b32_e32 v250, v92
	v_mov_b32_e32 v251, v93
	v_max_f32_e32 v76, 0, v76
	v_max_f32_e32 v78, 0, v78
	v_mul_f32_e32 v90, v82, v82
	v_max_f32_e32 v82, 0, v87
	v_mul_f32_e32 v82, v82, v82
	v_mul_f32_e32 v87, v83, v83
	v_max_f32_e32 v83, 0, v88
	v_mul_f32_e32 v88, v84, v84
	v_max_f32_e32 v84, 0, v89
	v_mul_f32_e32 v83, v83, v83
	v_mul_f32_e32 v84, v84, v84
	v_cvt_pk_bf16_f32 v82, v86, v82
	v_cvt_pk_bf16_f32 v83, v83, v84
	v_cvt_pk_bf16_f32 v84, v90, v87
	v_cvt_pk_bf16_f32 v85, v88, v85
	v_mov_b32_dpp v252, v248 row_ror:8 row_mask:0xf bank_mask:0xf
	v_mov_b32_dpp v226, v82 row_ror:8 row_mask:0xf bank_mask:0xf
	v_cndmask_b32_e64 v82, v82, v252, s[98:99]
	v_cndmask_b32_e64 v248, v226, v248, s[98:99]
	v_mov_b32_dpp v252, v249 row_ror:8 row_mask:0xf bank_mask:0xf
	v_mov_b32_dpp v226, v83 row_ror:8 row_mask:0xf bank_mask:0xf
	v_cndmask_b32_e64 v83, v83, v252, s[98:99]
	v_cndmask_b32_e64 v249, v226, v249, s[98:99]
	v_mov_b32_dpp v252, v250 row_ror:8 row_mask:0xf bank_mask:0xf
	v_mov_b32_dpp v226, v84 row_ror:8 row_mask:0xf bank_mask:0xf
	v_cndmask_b32_e64 v84, v84, v252, s[98:99]
	v_cndmask_b32_e64 v250, v226, v250, s[98:99]
	v_mov_b32_dpp v252, v251 row_ror:8 row_mask:0xf bank_mask:0xf
	v_mov_b32_dpp v226, v85 row_ror:8 row_mask:0xf bank_mask:0xf
	v_cndmask_b32_e64 v85, v85, v252, s[98:99]
	v_cndmask_b32_e64 v251, v226, v251, s[98:99]
	v_lshl_add_u64 v[226:227], v[98:99], 0, s[100:101]
	flat_store_dwordx4 v[98:99], v[248:251] nt
	flat_store_dwordx4 v[226:227], v[82:85] nt
	v_max_f32_e32 v77, 0, v77
	v_pk_mul_f32 v[68:69], v[68:69], v[152:153] op_sel_hi:[1,0]
	v_or_b32_e32 v82, 48, v150
	v_ashrrev_i32_e32 v83, 31, v82
	v_lshlrev_b64 v[82:83], 13, v[82:83]
	v_mul_f32_e32 v84, v74, v74
	v_max_f32_e32 v74, 0, v79
	v_lshl_add_u64 v[82:83], s[42:43], 0, v[82:83]
	v_mul_f32_e32 v74, v74, v74
	v_mul_f32_e32 v79, v75, v75
	v_max_f32_e32 v75, 0, v80
	v_mul_f32_e32 v80, v76, v76
	v_max_f32_e32 v76, 0, v81
	v_pk_mul_f32 v[66:67], v[66:67], v[152:153] op_sel_hi:[1,0]
	v_lshl_add_u64 v[82:83], v[82:83], 0, v[156:157]
	v_mul_f32_e32 v78, v78, v78
	v_mul_f32_e32 v75, v75, v75
	v_mul_f32_e32 v76, v76, v76
	v_mul_f32_e32 v77, v77, v77
	v_cvt_pk_bf16_f32 v74, v78, v74
	v_pk_mul_f32 v[72:73], v[72:73], v[152:153] op_sel_hi:[1,0]
	v_pk_mul_f32 v[70:71], v[70:71], v[152:153] op_sel_hi:[1,0]
	v_max_f32_e32 v66, 0, v66
	v_max_f32_e32 v67, 0, v67
	v_max_f32_e32 v68, 0, v68
	v_cvt_pk_bf16_f32 v75, v75, v76
	v_cvt_pk_bf16_f32 v76, v84, v79
	v_cvt_pk_bf16_f32 v77, v80, v77
	v_mov_b32_e32 v248, v74
	v_mov_b32_e32 v249, v75
	v_mov_b32_e32 v250, v76
	v_mov_b32_e32 v251, v77
	v_max_f32_e32 v70, 0, v70
	v_max_f32_e32 v69, 0, v69
	v_mul_f32_e32 v74, v66, v66
	v_max_f32_e32 v66, 0, v71
	v_mul_f32_e32 v71, v67, v67
	v_max_f32_e32 v67, 0, v72
	v_mul_f32_e32 v72, v68, v68
	v_max_f32_e32 v68, 0, v73
	v_mul_f32_e32 v66, v66, v66
	v_mul_f32_e32 v67, v67, v67
	v_mul_f32_e32 v68, v68, v68
	v_pk_mul_f32 v[58:59], v[58:59], v[148:149] op_sel_hi:[1,0]
	v_mul_f32_e32 v70, v70, v70
	v_mul_f32_e32 v69, v69, v69
	v_cvt_pk_bf16_f32 v66, v70, v66
	v_cvt_pk_bf16_f32 v67, v67, v68
	v_cvt_pk_bf16_f32 v68, v74, v71
	v_pk_mul_f32 v[62:63], v[62:63], v[148:149] op_sel_hi:[1,0]
	v_pk_mul_f32 v[60:61], v[60:61], v[148:149] op_sel_hi:[1,0]
	v_max_f32_e32 v58, 0, v58
	v_cvt_pk_bf16_f32 v69, v72, v69
	v_mov_b32_dpp v252, v248 row_ror:8 row_mask:0xf bank_mask:0xf
	v_mov_b32_dpp v226, v66 row_ror:8 row_mask:0xf bank_mask:0xf
	v_cndmask_b32_e64 v66, v66, v252, s[98:99]
	v_cndmask_b32_e64 v248, v226, v248, s[98:99]
	v_mov_b32_dpp v252, v249 row_ror:8 row_mask:0xf bank_mask:0xf
	v_mov_b32_dpp v226, v67 row_ror:8 row_mask:0xf bank_mask:0xf
	v_cndmask_b32_e64 v67, v67, v252, s[98:99]
	v_cndmask_b32_e64 v249, v226, v249, s[98:99]
	v_mov_b32_dpp v252, v250 row_ror:8 row_mask:0xf bank_mask:0xf
	v_mov_b32_dpp v226, v68 row_ror:8 row_mask:0xf bank_mask:0xf
	v_cndmask_b32_e64 v68, v68, v252, s[98:99]
	v_cndmask_b32_e64 v250, v226, v250, s[98:99]
	v_mov_b32_dpp v252, v251 row_ror:8 row_mask:0xf bank_mask:0xf
	v_mov_b32_dpp v226, v69 row_ror:8 row_mask:0xf bank_mask:0xf
	v_cndmask_b32_e64 v69, v69, v252, s[98:99]
	v_cndmask_b32_e64 v251, v226, v251, s[98:99]
	v_lshl_add_u64 v[226:227], v[82:83], 0, s[100:101]
	flat_store_dwordx4 v[82:83], v[248:251] nt
	flat_store_dwordx4 v[226:227], v[66:69] nt
	v_pk_mul_f32 v[64:65], v[64:65], v[148:149] op_sel_hi:[1,0]
	v_max_f32_e32 v62, 0, v62
	v_mul_f32_e32 v68, v58, v58
	v_max_f32_e32 v58, 0, v63
	v_max_f32_e32 v59, 0, v59
	v_max_f32_e32 v60, 0, v60
	v_lshl_add_u64 v[66:67], v[142:143], 0, s[12:13]
	v_mul_f32_e32 v62, v62, v62
	v_mul_f32_e32 v58, v58, v58
	v_mul_f32_e32 v63, v59, v59
	v_max_f32_e32 v59, 0, v64
	v_mul_f32_e32 v64, v60, v60
	v_max_f32_e32 v60, 0, v65
	s_mov_b32 s12, 0x100000
	v_mul_f32_e32 v59, v59, v59
	v_max_f32_e32 v61, 0, v61
	v_mul_f32_e32 v60, v60, v60
	v_cvt_pk_bf16_f32 v58, v62, v58
	v_add_co_u32_e32 v62, vcc, s12, v142
	v_pk_mul_f32 v[52:53], v[52:53], v[148:149] op_sel_hi:[1,0]
	v_pk_mul_f32 v[50:51], v[50:51], v[148:149] op_sel_hi:[1,0]
	v_mul_f32_e32 v61, v61, v61
	v_cvt_pk_bf16_f32 v59, v59, v60
	v_cvt_pk_bf16_f32 v60, v68, v63
	v_addc_co_u32_e32 v63, vcc, 0, v143, vcc
	v_pk_mul_f32 v[56:57], v[56:57], v[148:149] op_sel_hi:[1,0]
	v_pk_mul_f32 v[54:55], v[54:55], v[148:149] op_sel_hi:[1,0]
	v_max_f32_e32 v50, 0, v50
	v_max_f32_e32 v51, 0, v51
	v_max_f32_e32 v52, 0, v52
	v_cvt_pk_bf16_f32 v61, v64, v61
	v_mov_b32_e32 v248, v58
	v_mov_b32_e32 v249, v59
	v_mov_b32_e32 v250, v60
	v_mov_b32_e32 v251, v61
	v_max_f32_e32 v54, 0, v54
	v_max_f32_e32 v53, 0, v53
	v_mul_f32_e32 v58, v50, v50
	v_max_f32_e32 v50, 0, v55
	v_mul_f32_e32 v55, v51, v51
	v_max_f32_e32 v51, 0, v56
	v_mul_f32_e32 v56, v52, v52
	v_max_f32_e32 v52, 0, v57
	v_mul_f32_e32 v50, v50, v50
	v_mul_f32_e32 v51, v51, v51
	v_mul_f32_e32 v52, v52, v52
	v_pk_mul_f32 v[42:43], v[42:43], v[146:147] op_sel_hi:[1,0]
	v_mul_f32_e32 v54, v54, v54
	v_mul_f32_e32 v53, v53, v53
	v_cvt_pk_bf16_f32 v50, v54, v50
	v_cvt_pk_bf16_f32 v51, v51, v52
	v_cvt_pk_bf16_f32 v52, v58, v55
	v_pk_mul_f32 v[46:47], v[46:47], v[146:147] op_sel_hi:[1,0]
	v_pk_mul_f32 v[44:45], v[44:45], v[146:147] op_sel_hi:[1,0]
	v_max_f32_e32 v42, 0, v42
	v_cvt_pk_bf16_f32 v53, v56, v53
	v_mov_b32_dpp v252, v248 row_ror:8 row_mask:0xf bank_mask:0xf
	v_mov_b32_dpp v226, v50 row_ror:8 row_mask:0xf bank_mask:0xf
	v_cndmask_b32_e64 v50, v50, v252, s[98:99]
	v_cndmask_b32_e64 v248, v226, v248, s[98:99]
	v_mov_b32_dpp v252, v249 row_ror:8 row_mask:0xf bank_mask:0xf
	v_mov_b32_dpp v226, v51 row_ror:8 row_mask:0xf bank_mask:0xf
	v_cndmask_b32_e64 v51, v51, v252, s[98:99]
	v_cndmask_b32_e64 v249, v226, v249, s[98:99]
	v_mov_b32_dpp v252, v250 row_ror:8 row_mask:0xf bank_mask:0xf
	v_mov_b32_dpp v226, v52 row_ror:8 row_mask:0xf bank_mask:0xf
	v_cndmask_b32_e64 v52, v52, v252, s[98:99]
	v_cndmask_b32_e64 v250, v226, v250, s[98:99]
	v_mov_b32_dpp v252, v251 row_ror:8 row_mask:0xf bank_mask:0xf
	v_mov_b32_dpp v226, v53 row_ror:8 row_mask:0xf bank_mask:0xf
	v_cndmask_b32_e64 v53, v53, v252, s[98:99]
	v_cndmask_b32_e64 v251, v226, v251, s[98:99]
	v_lshl_add_u64 v[226:227], v[66:67], 0, s[100:101]
	flat_store_dwordx4 v[66:67], v[248:251] nt
	flat_store_dwordx4 v[226:227], v[50:53] nt
	s_mov_b64 s[12:13], 0x120000
	v_pk_mul_f32 v[48:49], v[48:49], v[146:147] op_sel_hi:[1,0]
	v_max_f32_e32 v46, 0, v46
	v_mul_f32_e32 v52, v42, v42
	v_max_f32_e32 v42, 0, v47
	v_max_f32_e32 v43, 0, v43
	v_max_f32_e32 v44, 0, v44
	v_lshl_add_u64 v[50:51], v[142:143], 0, s[12:13]
	v_mul_f32_e32 v46, v46, v46
	v_mul_f32_e32 v42, v42, v42
	v_mul_f32_e32 v47, v43, v43
	v_max_f32_e32 v43, 0, v48
	v_mul_f32_e32 v48, v44, v44
	v_max_f32_e32 v44, 0, v49
	s_mov_b32 s12, 0x120000
	v_mul_f32_e32 v43, v43, v43
	v_max_f32_e32 v45, 0, v45
	v_mul_f32_e32 v44, v44, v44
	v_cvt_pk_bf16_f32 v42, v46, v42
	v_add_co_u32_e32 v46, vcc, s12, v142
	v_pk_mul_f32 v[36:37], v[36:37], v[146:147] op_sel_hi:[1,0]
	v_pk_mul_f32 v[34:35], v[34:35], v[146:147] op_sel_hi:[1,0]
	v_mul_f32_e32 v45, v45, v45
	v_cvt_pk_bf16_f32 v43, v43, v44
	v_cvt_pk_bf16_f32 v44, v52, v47
	v_addc_co_u32_e32 v47, vcc, 0, v143, vcc
	v_pk_mul_f32 v[40:41], v[40:41], v[146:147] op_sel_hi:[1,0]
	v_pk_mul_f32 v[38:39], v[38:39], v[146:147] op_sel_hi:[1,0]
	v_max_f32_e32 v34, 0, v34
	v_max_f32_e32 v35, 0, v35
	v_max_f32_e32 v36, 0, v36
	v_cvt_pk_bf16_f32 v45, v48, v45
	v_mov_b32_e32 v248, v42
	v_mov_b32_e32 v249, v43
	v_mov_b32_e32 v250, v44
	v_mov_b32_e32 v251, v45
	v_max_f32_e32 v38, 0, v38
	v_max_f32_e32 v37, 0, v37
	v_mul_f32_e32 v42, v34, v34
	v_max_f32_e32 v34, 0, v39
	v_mul_f32_e32 v39, v35, v35
	v_max_f32_e32 v35, 0, v40
	v_mul_f32_e32 v40, v36, v36
	v_max_f32_e32 v36, 0, v41
	v_mul_f32_e32 v34, v34, v34
	v_mul_f32_e32 v35, v35, v35
	v_mul_f32_e32 v36, v36, v36
	v_pk_mul_f32 v[26:27], v[26:27], v[144:145] op_sel_hi:[1,0]
	v_mul_f32_e32 v38, v38, v38
	v_mul_f32_e32 v37, v37, v37
	v_cvt_pk_bf16_f32 v34, v38, v34
	v_cvt_pk_bf16_f32 v35, v35, v36
	v_cvt_pk_bf16_f32 v36, v42, v39
	v_pk_mul_f32 v[30:31], v[30:31], v[144:145] op_sel_hi:[1,0]
	v_pk_mul_f32 v[28:29], v[28:29], v[144:145] op_sel_hi:[1,0]
	v_max_f32_e32 v26, 0, v26
	v_cvt_pk_bf16_f32 v37, v40, v37
	v_mov_b32_dpp v252, v248 row_ror:8 row_mask:0xf bank_mask:0xf
	v_mov_b32_dpp v226, v34 row_ror:8 row_mask:0xf bank_mask:0xf
	v_cndmask_b32_e64 v34, v34, v252, s[98:99]
	v_cndmask_b32_e64 v248, v226, v248, s[98:99]
	v_mov_b32_dpp v252, v249 row_ror:8 row_mask:0xf bank_mask:0xf
	v_mov_b32_dpp v226, v35 row_ror:8 row_mask:0xf bank_mask:0xf
	v_cndmask_b32_e64 v35, v35, v252, s[98:99]
	v_cndmask_b32_e64 v249, v226, v249, s[98:99]
	v_mov_b32_dpp v252, v250 row_ror:8 row_mask:0xf bank_mask:0xf
	v_mov_b32_dpp v226, v36 row_ror:8 row_mask:0xf bank_mask:0xf
	v_cndmask_b32_e64 v36, v36, v252, s[98:99]
	v_cndmask_b32_e64 v250, v226, v250, s[98:99]
	v_mov_b32_dpp v252, v251 row_ror:8 row_mask:0xf bank_mask:0xf
	v_mov_b32_dpp v226, v37 row_ror:8 row_mask:0xf bank_mask:0xf
	v_cndmask_b32_e64 v37, v37, v252, s[98:99]
	v_cndmask_b32_e64 v251, v226, v251, s[98:99]
	v_lshl_add_u64 v[226:227], v[50:51], 0, s[100:101]
	flat_store_dwordx4 v[50:51], v[248:251] nt
	flat_store_dwordx4 v[226:227], v[34:37] nt
	s_mov_b64 s[12:13], 0x140000
	v_pk_mul_f32 v[32:33], v[32:33], v[144:145] op_sel_hi:[1,0]
	v_max_f32_e32 v30, 0, v30
	v_mul_f32_e32 v36, v26, v26
	v_max_f32_e32 v26, 0, v31
	v_max_f32_e32 v27, 0, v27
	v_max_f32_e32 v28, 0, v28
	v_lshl_add_u64 v[34:35], v[142:143], 0, s[12:13]
	v_mul_f32_e32 v30, v30, v30
	v_mul_f32_e32 v26, v26, v26
	v_mul_f32_e32 v31, v27, v27
	v_max_f32_e32 v27, 0, v32
	v_mul_f32_e32 v32, v28, v28
	v_max_f32_e32 v28, 0, v33
	s_mov_b32 s12, 0x140000
	v_mul_f32_e32 v27, v27, v27
	v_max_f32_e32 v29, 0, v29
	v_mul_f32_e32 v28, v28, v28
	v_cvt_pk_bf16_f32 v26, v30, v26
	v_add_co_u32_e32 v30, vcc, s12, v142
	v_pk_mul_f32 v[20:21], v[20:21], v[144:145] op_sel_hi:[1,0]
	v_pk_mul_f32 v[18:19], v[18:19], v[144:145] op_sel_hi:[1,0]
	v_mul_f32_e32 v29, v29, v29
	v_cvt_pk_bf16_f32 v27, v27, v28
	v_cvt_pk_bf16_f32 v28, v36, v31
	v_addc_co_u32_e32 v31, vcc, 0, v143, vcc
	v_pk_mul_f32 v[24:25], v[24:25], v[144:145] op_sel_hi:[1,0]
	v_pk_mul_f32 v[22:23], v[22:23], v[144:145] op_sel_hi:[1,0]
	v_max_f32_e32 v18, 0, v18
	v_max_f32_e32 v19, 0, v19
	v_max_f32_e32 v20, 0, v20
	v_cvt_pk_bf16_f32 v29, v32, v29
	v_mov_b32_e32 v248, v26
	v_mov_b32_e32 v249, v27
	v_mov_b32_e32 v250, v28
	v_mov_b32_e32 v251, v29
	v_max_f32_e32 v22, 0, v22
	v_max_f32_e32 v21, 0, v21
	v_mul_f32_e32 v26, v18, v18
	v_max_f32_e32 v18, 0, v23
	v_mul_f32_e32 v23, v19, v19
	v_max_f32_e32 v19, 0, v24
	v_mul_f32_e32 v24, v20, v20
	v_max_f32_e32 v20, 0, v25
	v_mul_f32_e32 v18, v18, v18
	v_mul_f32_e32 v19, v19, v19
	v_mul_f32_e32 v20, v20, v20
	v_pk_mul_f32 v[10:11], v[10:11], v[140:141] op_sel_hi:[1,0]
	v_mul_f32_e32 v22, v22, v22
	v_mul_f32_e32 v21, v21, v21
	v_cvt_pk_bf16_f32 v18, v22, v18
	v_cvt_pk_bf16_f32 v19, v19, v20
	v_cvt_pk_bf16_f32 v20, v26, v23
	v_pk_mul_f32 v[14:15], v[14:15], v[140:141] op_sel_hi:[1,0]
	v_pk_mul_f32 v[12:13], v[12:13], v[140:141] op_sel_hi:[1,0]
	v_max_f32_e32 v10, 0, v10
	v_cvt_pk_bf16_f32 v21, v24, v21
	v_mov_b32_dpp v252, v248 row_ror:8 row_mask:0xf bank_mask:0xf
	v_mov_b32_dpp v226, v18 row_ror:8 row_mask:0xf bank_mask:0xf
	v_cndmask_b32_e64 v18, v18, v252, s[98:99]
	v_cndmask_b32_e64 v248, v226, v248, s[98:99]
	v_mov_b32_dpp v252, v249 row_ror:8 row_mask:0xf bank_mask:0xf
	v_mov_b32_dpp v226, v19 row_ror:8 row_mask:0xf bank_mask:0xf
	v_cndmask_b32_e64 v19, v19, v252, s[98:99]
	v_cndmask_b32_e64 v249, v226, v249, s[98:99]
	v_mov_b32_dpp v252, v250 row_ror:8 row_mask:0xf bank_mask:0xf
	v_mov_b32_dpp v226, v20 row_ror:8 row_mask:0xf bank_mask:0xf
	v_cndmask_b32_e64 v20, v20, v252, s[98:99]
	v_cndmask_b32_e64 v250, v226, v250, s[98:99]
	v_mov_b32_dpp v252, v251 row_ror:8 row_mask:0xf bank_mask:0xf
	v_mov_b32_dpp v226, v21 row_ror:8 row_mask:0xf bank_mask:0xf
	v_cndmask_b32_e64 v21, v21, v252, s[98:99]
	v_cndmask_b32_e64 v251, v226, v251, s[98:99]
	v_lshl_add_u64 v[226:227], v[34:35], 0, s[100:101]
	flat_store_dwordx4 v[34:35], v[248:251] nt
	flat_store_dwordx4 v[226:227], v[18:21] nt
	s_mov_b64 s[12:13], 0x160000
	v_pk_mul_f32 v[16:17], v[16:17], v[140:141] op_sel_hi:[1,0]
	v_max_f32_e32 v14, 0, v14
	v_mul_f32_e32 v20, v10, v10
	v_max_f32_e32 v10, 0, v15
	v_max_f32_e32 v11, 0, v11
	v_max_f32_e32 v12, 0, v12
	v_lshl_add_u64 v[18:19], v[142:143], 0, s[12:13]
	v_mul_f32_e32 v14, v14, v14
	v_mul_f32_e32 v10, v10, v10
	v_mul_f32_e32 v15, v11, v11
	v_max_f32_e32 v11, 0, v16
	v_mul_f32_e32 v16, v12, v12
	v_max_f32_e32 v12, 0, v17
	s_mov_b32 s12, 0x160000
	v_mul_f32_e32 v11, v11, v11
	v_max_f32_e32 v13, 0, v13
	v_mul_f32_e32 v12, v12, v12
	v_cvt_pk_bf16_f32 v10, v14, v10
	v_add_co_u32_e32 v14, vcc, s12, v142
	v_pk_mul_f32 v[4:5], v[4:5], v[140:141] op_sel_hi:[1,0]
	v_pk_mul_f32 v[2:3], v[2:3], v[140:141] op_sel_hi:[1,0]
	v_mul_f32_e32 v13, v13, v13
	v_cvt_pk_bf16_f32 v11, v11, v12
	v_cvt_pk_bf16_f32 v12, v20, v15
	v_addc_co_u32_e32 v15, vcc, 0, v143, vcc
	v_pk_mul_f32 v[8:9], v[8:9], v[140:141] op_sel_hi:[1,0]
	v_pk_mul_f32 v[6:7], v[6:7], v[140:141] op_sel_hi:[1,0]
	v_max_f32_e32 v2, 0, v2
	v_max_f32_e32 v3, 0, v3
	v_max_f32_e32 v4, 0, v4
	v_cvt_pk_bf16_f32 v13, v16, v13
	v_mov_b32_e32 v248, v10
	v_mov_b32_e32 v249, v11
	v_mov_b32_e32 v250, v12
	v_mov_b32_e32 v251, v13
	v_max_f32_e32 v5, 0, v5
	v_max_f32_e32 v6, 0, v6
	v_mul_f32_e32 v10, v2, v2
	v_max_f32_e32 v2, 0, v7
	v_mul_f32_e32 v7, v3, v3
	v_max_f32_e32 v3, 0, v8
	v_mul_f32_e32 v8, v4, v4
	v_max_f32_e32 v4, 0, v9
	v_mul_f32_e32 v2, v2, v2
	v_mul_f32_e32 v3, v3, v3
	v_mul_f32_e32 v4, v4, v4
	v_mul_f32_e32 v5, v5, v5
	s_mov_b64 s[12:13], -1
	s_andn2_b64 vcc, exec, s[40:41]
	v_mul_f32_e32 v6, v6, v6
	v_cvt_pk_bf16_f32 v2, v6, v2
	v_cvt_pk_bf16_f32 v3, v3, v4
	v_cvt_pk_bf16_f32 v4, v10, v7
	v_cvt_pk_bf16_f32 v5, v8, v5
	v_mov_b32_dpp v252, v248 row_ror:8 row_mask:0xf bank_mask:0xf
	v_mov_b32_dpp v226, v2 row_ror:8 row_mask:0xf bank_mask:0xf
	v_cndmask_b32_e64 v2, v2, v252, s[98:99]
	v_cndmask_b32_e64 v248, v226, v248, s[98:99]
	v_mov_b32_dpp v252, v249 row_ror:8 row_mask:0xf bank_mask:0xf
	v_mov_b32_dpp v226, v3 row_ror:8 row_mask:0xf bank_mask:0xf
	v_cndmask_b32_e64 v3, v3, v252, s[98:99]
	v_cndmask_b32_e64 v249, v226, v249, s[98:99]
	v_mov_b32_dpp v252, v250 row_ror:8 row_mask:0xf bank_mask:0xf
	v_mov_b32_dpp v226, v4 row_ror:8 row_mask:0xf bank_mask:0xf
	v_cndmask_b32_e64 v4, v4, v252, s[98:99]
	v_cndmask_b32_e64 v250, v226, v250, s[98:99]
	v_mov_b32_dpp v252, v251 row_ror:8 row_mask:0xf bank_mask:0xf
	v_mov_b32_dpp v226, v5 row_ror:8 row_mask:0xf bank_mask:0xf
	v_cndmask_b32_e64 v5, v5, v252, s[98:99]
	v_cndmask_b32_e64 v251, v226, v251, s[98:99]
	v_lshl_add_u64 v[226:227], v[18:19], 0, s[100:101]
	flat_store_dwordx4 v[18:19], v[248:251] nt
	flat_store_dwordx4 v[226:227], v[2:5] nt
	s_cbranch_vccnz .LBB0_553
	s_andn2_b64 vcc, exec, s[18:19]
	s_cbranch_vccnz .LBB0_552
	s_barrier
	s_branch .LBB0_552

	.amdhsa_kernel _Z9trunk_fwd4Args
		.amdhsa_group_segment_fixed_size 0
		.amdhsa_private_segment_fixed_size 0
		.amdhsa_kernarg_size 432
		.amdhsa_user_sgpr_count 2
		.amdhsa_user_sgpr_dispatch_ptr 0
		.amdhsa_user_sgpr_queue_ptr 0
		.amdhsa_user_sgpr_kernarg_segment_ptr 1
		.amdhsa_user_sgpr_dispatch_id 0
		.amdhsa_user_sgpr_kernarg_preload_length 0
		.amdhsa_user_sgpr_kernarg_preload_offset 0
		.amdhsa_user_sgpr_private_segment_size 0
		.amdhsa_uses_dynamic_stack 0
		.amdhsa_enable_private_segment 0
		.amdhsa_system_sgpr_workgroup_id_x 1
		.amdhsa_system_sgpr_workgroup_id_y 0
		.amdhsa_system_sgpr_workgroup_id_z 0
		.amdhsa_system_sgpr_workgroup_info 0
		.amdhsa_system_vgpr_workitem_id 2
		.amdhsa_next_free_vgpr 256
		.amdhsa_next_free_sgpr 102
		.amdhsa_accum_offset 256
		.amdhsa_reserve_vcc 1
		.amdhsa_float_round_mode_32 0
		.amdhsa_float_round_mode_16_64 0
		.amdhsa_float_denorm_mode_32 3
		.amdhsa_float_denorm_mode_16_64 3
		.amdhsa_dx10_clamp 1
		.amdhsa_ieee_mode 1
		.amdhsa_fp16_overflow 0
		.amdhsa_tg_split 0
		.amdhsa_exception_fp_ieee_invalid_op 0
		.amdhsa_exception_fp_denorm_src 0
		.amdhsa_exception_fp_ieee_div_zero 0
		.amdhsa_exception_fp_ieee_overflow 0
		.amdhsa_exception_fp_ieee_underflow 0
		.amdhsa_exception_fp_ieee_inexact 0
		.amdhsa_exception_int_div_zero 0
	.end_amdhsa_kernel

amdhsa.kernels:
  - .agpr_count:     0
    .args:
      - .offset:         0
        .size:           176
        .value_kind:     by_value
      - .offset:         176
        .size:           4
        .value_kind:     hidden_block_count_x
      - .offset:         180
        .size:           4
        .value_kind:     hidden_block_count_y
      - .offset:         184
        .size:           4
        .value_kind:     hidden_block_count_z
      - .offset:         188
        .size:           2
        .value_kind:     hidden_group_size_x
      - .offset:         190
        .size:           2
        .value_kind:     hidden_group_size_y
      - .offset:         192
        .size:           2
        .value_kind:     hidden_group_size_z
      - .offset:         194
        .size:           2
        .value_kind:     hidden_remainder_x
      - .offset:         196
        .size:           2
        .value_kind:     hidden_remainder_y
      - .offset:         198
        .size:           2
        .value_kind:     hidden_remainder_z
      - .offset:         216
        .size:           8
        .value_kind:     hidden_global_offset_x
      - .offset:         224
        .size:           8
        .value_kind:     hidden_global_offset_y
      - .offset:         232
        .size:           8
        .value_kind:     hidden_global_offset_z
      - .offset:         240
        .size:           2
        .value_kind:     hidden_grid_dims
      - .offset:         264
        .size:           8
        .value_kind:     hidden_multigrid_sync_arg
      - .offset:         296
        .size:           4
        .value_kind:     hidden_dynamic_lds_size
    .group_segment_fixed_size: 0
    .kernarg_segment_align: 8
    .kernarg_segment_size: 432
    .language:       OpenCL C
    .language_version:
      - 2
      - 0
    .max_flat_workgroup_size: 512
    .name:           _Z9trunk_fwd4Args
    .private_segment_fixed_size: 0
    .sgpr_count:     108
    .sgpr_spill_count: 181
    .symbol:         _Z9trunk_fwd4Args.kd
    .uniform_work_group_size: 1
    .uses_dynamic_stack: false
    .vgpr_count:     256
    .vgpr_spill_count: 0
    .wavefront_size: 64
